# attention: task->workgroup permutation so the 16 blocks of one (b,h,group) run together on one XCD (shared K/V rows hit L2)
# baseline (speedup 1.0000x reference)
; #define LAS __attribute__((address_space(3)))
; __global__ void __launch_bounds__(NTHREADS, 2) fwd_megakernel(Args A) {
;     extern __shared__ __attribute__((aligned(16))) unsigned char lds_raw[];
;     LAS unsigned char* lds = (LAS unsigned char*)lds_raw;
;     cg::grid_group grid = cg::this_grid();
;     const int tid = threadIdx.x, lane = tid & 63, wave = __builtin_amdgcn_readfirstlane(tid >> 6);
;     const int G = gridDim.x, bx = blockIdx.x;
;     const int gw = bx * NWAVES + wave, NGW = G * NWAVES;
;     unsigned char* ws = A.ws;
;     float* ssq = (float*)(ws + WS_CTL);
;     float* vs1 = ssq + 4 * MROWS; float* vs2 = vs1 + MROWS;
;     bf16* WIN = (bf16*)(ws + WS_WIN); bf16* WOUT = (bf16*)(ws + WS_WOUT); bf16* XB = (bf16*)(ws + WS_XB); bf16* Y = (bf16*)(ws + WS_Y);
;     bf16* PROJ = (bf16*)(ws + WS_PROJ); bf16* EXTRA = (bf16*)(ws + WS_EXTRA); float* LSE = (float*)(ws + WS_LSE);
;     constexpr size_t PLANE = (size_t)MROWS * DM;
;     bf16* W_BO = (bf16*)A.out + (size_t)20 * MiB; bf16* W_CI = (bf16*)A.out + (size_t)21 * MiB; bf16* W_CO = (bf16*)A.out + (size_t)24 * MiB; bf16* W_A1 = (bf16*)A.out + (size_t)25 * MiB;
;     volatile LAS unsigned* xst = (volatile LAS unsigned*)(lds + LDS_BYTES - 64);
;     if (tid < 16) xst[tid] = 0u;
;     __syncthreads();
;     const XcdBarrier xbar = xcd_barrier_post((unsigned*)(ws + WS_BAR), xst);
.LBB0_109:
	s_or_b64 exec, exec, s[4:5]
	s_load_dwordx16 s[4:19], s[0:1], 0x40
	s_add_u32 s0, s82, 0x40000
	s_addc_u32 s1, s83, 0
	v_lshl_add_u64 v[0:1], v[0:1], 2, s[2:3]
	s_mov_b64 s[2:3], 0x1400
	s_waitcnt lgkmcnt(0)
	v_writelane_b32 v251, s4, 5
	v_lshl_add_u64 v[140:141], v[0:1], 0, s[2:3]
	s_mov_b64 s[2:3], 0x2400
	v_writelane_b32 v251, s5, 6
	v_writelane_b32 v251, s6, 7
	v_writelane_b32 v251, s7, 8
	v_writelane_b32 v251, s8, 9
	v_writelane_b32 v251, s9, 10
	v_writelane_b32 v251, s10, 11
	v_writelane_b32 v251, s11, 12
	v_writelane_b32 v251, s12, 13
	v_writelane_b32 v251, s13, 14
	v_writelane_b32 v251, s14, 15
	v_writelane_b32 v251, s15, 16
	v_writelane_b32 v251, s16, 17
	v_writelane_b32 v251, s17, 18
	v_writelane_b32 v251, s18, 19
	v_writelane_b32 v251, s19, 20
	v_writelane_b32 v251, s0, 21
	v_lshl_add_u64 v[142:143], v[0:1], 0, s[2:3]
	v_mov_b32_e32 v0, 0x200
	v_writelane_b32 v251, s1, 22
	s_add_u32 s0, s82, 0x50000
	s_addc_u32 s1, s83, 0
	s_add_u32 s54, s82, 0x1700000
	s_addc_u32 s55, s83, 0
	s_add_u32 s14, s82, 0x3700000
	s_addc_u32 s15, s83, 0
	s_add_u32 s34, s82, 0x5700000
	s_addc_u32 s35, s83, 0
	s_add_u32 s24, s82, 0xe700000
	v_writelane_b32 v251, s0, 23
	s_addc_u32 s25, s83, 0
	v_and_b32_e32 v1, 0x7f, v145
	v_writelane_b32 v251, s1, 24
	s_add_u32 s0, s82, 0xf700000
	s_addc_u32 s1, s83, 0
	s_add_u32 s16, s80, 0x2800000
	s_addc_u32 s17, s81, 0
	s_add_u32 s18, s80, 0x2a00000
	s_addc_u32 s19, s81, 0
	s_add_u32 s20, s80, 0x3000000
	v_writelane_b32 v251, s0, 25
	s_addc_u32 s21, s81, 0
	v_bfe_u32 v2, v145, 3, 4
	v_writelane_b32 v251, s1, 26
	s_add_u32 s0, s80, 0x3200000
	s_addc_u32 s1, s81, 0
	v_writelane_b32 v251, s0, 27
	v_lshlrev_b32_e32 v144, 3, v1
	v_mov_b32_e32 v139, 0x358637bd
	v_writelane_b32 v251, s1, 28
	s_add_u32 s0, s82, 0x10000
	s_addc_u32 s1, s83, 0
	v_writelane_b32 v251, s0, 29
	s_cmpk_lt_i32 s90, 0x500
	v_mov_b32_e32 v190, 1
	v_writelane_b32 v251, s1, 30
	s_cselect_b64 s[0:1], -1, 0
	v_writelane_b32 v251, s0, 31
	s_ashr_i32 s4, s84, 31
	v_lshlrev_b32_e32 v146, 2, v2
	v_writelane_b32 v251, s1, 32
	s_ashr_i32 s0, s90, 31
	v_writelane_b32 v251, s0, 33
	s_lshr_b32 s0, s0, 29
	s_add_i32 s1, s90, s0
	s_ashr_i32 s0, s1, 3
	s_and_b32 s1, s1, -8
	s_sub_i32 s1, s90, s1
	s_add_u32 s28, s82, 0x80200
	s_addc_u32 s29, s83, 0
	v_writelane_b32 v251, s4, 34
	s_add_u32 s4, s82, 0x80400
	s_addc_u32 s5, s83, 0
	v_writelane_b32 v251, s4, 35
	v_mov_b64_e32 v[148:149], 0x4ff
	v_mbcnt_hi_u32_b32 v191, -1, v12
	v_writelane_b32 v251, s5, 36
	s_add_u32 s4, s82, 0x80500
	s_addc_u32 s5, s83, 0
	v_writelane_b32 v251, s4, 37
	v_mov_b32_e32 v192, 0x42800000
	v_mov_b32_e32 v193, 0xf149f2ca
	v_writelane_b32 v251, s5, 38
	s_add_u32 s4, s82, 0x80600
	s_addc_u32 s5, s83, 0
	v_writelane_b32 v251, s4, 39
	v_mov_b32_e32 v194, 0x41b17218
	v_mov_b64_e32 v[160:161], 0x100
	v_writelane_b32 v251, s5, 40
	s_add_u32 s4, s82, 0x80700
	s_addc_u32 s5, s83, 0
	v_writelane_b32 v251, s4, 41
	v_mov_b64_e32 v[240:241], 0xff
	v_mov_b64_e32 v[242:243], 0x400
	v_writelane_b32 v251, s5, 42
	s_add_u32 s4, s82, 0x80800
	s_addc_u32 s5, s83, 0
	v_writelane_b32 v251, s4, 43
	v_mov_b32_e32 v195, 0x42a00000
	s_movk_i32 s91, 0x90
	v_writelane_b32 v251, s5, 44
	s_add_u32 s4, s82, 0x80900
	s_addc_u32 s5, s83, 0
	v_writelane_b32 v251, s4, 45
	s_barrier
	s_nop 0
	v_writelane_b32 v251, s5, 46
	s_add_u32 s4, s82, 0x80a00
	s_addc_u32 s5, s83, 0
	v_writelane_b32 v251, s4, 47
	s_nop 1
	v_writelane_b32 v251, s5, 48
	s_add_u32 s4, s82, 0x80b00
	s_addc_u32 s5, s83, 0
	v_writelane_b32 v251, s4, 49
	s_nop 1
	v_writelane_b32 v251, s5, 50
	s_add_u32 s4, s82, 0x80c00
	s_addc_u32 s5, s83, 0
	v_writelane_b32 v251, s4, 51
	s_nop 1
	v_writelane_b32 v251, s5, 52
	s_add_u32 s4, s82, 0x80d00
	s_addc_u32 s5, s83, 0
	v_writelane_b32 v251, s4, 53
	s_nop 1
	v_writelane_b32 v251, s5, 54
	s_add_u32 s4, s82, 0x80e00
	s_addc_u32 s5, s83, 0
	v_writelane_b32 v251, s4, 55
	s_nop 1
	v_writelane_b32 v251, s5, 56
	s_add_u32 s4, s82, 0x80f00
	s_addc_u32 s5, s83, 0
	v_writelane_b32 v251, s4, 57
	s_nop 1
	v_writelane_b32 v251, s5, 58
	s_add_u32 s4, s82, 0x81000
	s_addc_u32 s5, s83, 0
	v_writelane_b32 v251, s4, 59
	s_nop 1
	v_writelane_b32 v251, s5, 60
	s_add_u32 s4, s82, 0x81100
	s_addc_u32 s5, s83, 0
	v_writelane_b32 v251, s4, 61
	s_nop 1
	v_writelane_b32 v251, s5, 62
	s_add_u32 s4, s82, 0x81200
	s_addc_u32 s5, s83, 0
	v_writelane_b32 v251, s4, 63
	s_nop 1
	v_writelane_b32 v252, s5, 0
	s_add_u32 s4, s82, 0x81300
	s_addc_u32 s5, s83, 0
	v_writelane_b32 v252, s4, 1
	s_cmp_eq_u32 s48, 15
	s_nop 0
	v_writelane_b32 v252, s5, 2
	s_cselect_b64 s[4:5], -1, 0
	v_writelane_b32 v252, s4, 3
	s_cmp_eq_u32 s48, 14
	s_nop 0
	v_writelane_b32 v252, s5, 4
	s_cselect_b64 s[4:5], -1, 0
	v_writelane_b32 v252, s4, 5
	s_cmp_eq_u32 s48, 13
	s_nop 0
	v_writelane_b32 v252, s5, 6
	s_cselect_b64 s[4:5], -1, 0
	v_writelane_b32 v252, s4, 7
	s_cmp_eq_u32 s48, 12
	s_nop 0
	v_writelane_b32 v252, s5, 8
	s_cselect_b64 s[4:5], -1, 0
	v_writelane_b32 v252, s4, 9
	s_cmp_eq_u32 s48, 11
	s_nop 0
	v_writelane_b32 v252, s5, 10
	s_cselect_b64 s[4:5], -1, 0
	v_writelane_b32 v252, s4, 11
	s_cmp_eq_u32 s48, 10
	s_nop 0
	v_writelane_b32 v252, s5, 12
	s_cselect_b64 s[4:5], -1, 0
	v_writelane_b32 v252, s4, 13
	s_cmp_eq_u32 s48, 9
	s_nop 0
	v_writelane_b32 v252, s5, 14
	s_cselect_b64 s[4:5], -1, 0
	v_writelane_b32 v252, s4, 15
	s_cmp_eq_u32 s48, 8
	s_nop 0
	v_writelane_b32 v252, s5, 16
	s_cselect_b64 s[4:5], -1, 0
	v_writelane_b32 v252, s4, 17
	s_cmp_eq_u32 s48, 7
	s_nop 0
	v_writelane_b32 v252, s5, 18
	s_cselect_b64 s[4:5], -1, 0
	v_writelane_b32 v252, s4, 19
	s_cmp_eq_u32 s48, 6
	s_nop 0
	v_writelane_b32 v252, s5, 20
	s_cselect_b64 s[4:5], -1, 0
	v_writelane_b32 v252, s4, 21
; __device__ __forceinline__ void attn_phase(LAS unsigned char* lds, const bf16* PROJ, const bf16* Ygate, bf16* OG0, bf16* OG1, bf16* OG2, float* LSE, const float* qnw, const float* knw, int bx, int G) {
;     ...
;     if (bx < 3072) AT_LOAD(bx, 0);
;     if (bx + G < 3072) AT_LOAD(bx + G, 1);
	s_cmp_eq_u32 s48, 5
	s_nop 0
	v_writelane_b32 v252, s5, 22
	s_cselect_b64 s[4:5], -1, 0
	v_writelane_b32 v252, s4, 23
	s_cmp_eq_u32 s48, 4
	s_nop 0
	v_writelane_b32 v252, s5, 24
	s_cselect_b64 s[4:5], -1, 0
	v_writelane_b32 v252, s4, 25
	s_cmp_eq_u32 s48, 3
	s_nop 0
	v_writelane_b32 v252, s5, 26
	s_cselect_b64 s[4:5], -1, 0
	v_writelane_b32 v252, s4, 27
	s_cmp_eq_u32 s48, 2
	s_nop 0
	v_writelane_b32 v252, s5, 28
	s_cselect_b64 s[4:5], -1, 0
	v_writelane_b32 v252, s4, 29
	s_cmp_eq_u32 s48, 1
	s_nop 0
	v_writelane_b32 v252, s5, 30
	s_cselect_b64 s[4:5], -1, 0
	v_writelane_b32 v252, s4, 31
	s_cmp_eq_u32 s48, 0
	s_nop 0
	v_writelane_b32 v252, s5, 32
	s_cselect_b64 s[4:5], -1, 0
	v_writelane_b32 v252, s4, 33
	s_nop 1
	v_writelane_b32 v252, s5, 34
	s_add_u32 s4, s82, 0x83400
	s_addc_u32 s5, s83, 0
	v_writelane_b32 v252, s4, 35
	s_nop 1
	v_writelane_b32 v252, s5, 36
	s_add_u32 s4, s82, 0x83500
	s_addc_u32 s5, s83, 0
	v_writelane_b32 v252, s4, 37
	s_nop 1
	v_writelane_b32 v252, s5, 38
	s_add_u32 s4, s80, 0x1000000
	s_addc_u32 s5, s81, 0
	v_writelane_b32 v252, s4, 39
	s_lshr_b32 s100, s90, 3
	s_and_b32 s100, s100, 15
	s_and_b32 s101, s90, 7
	s_lshl_b32 s101, s101, 4
	s_or_b32 s100, s100, s101
	s_and_b32 s101, s90, 0x80
	s_or_b32 s100, s100, s101
	s_cmp_eq_u32 s84, 0x100
	s_cselect_b32 s100, s100, s90
	s_cmpk_lt_i32 s100, 0xc00
	s_nop 0
	v_writelane_b32 v252, s5, 40
	s_cselect_b64 s[4:5], -1, 0
	v_writelane_b32 v252, s4, 41
	s_and_b32 s8, s100, 15
	s_nop 0
	v_writelane_b32 v252, s5, 42
	s_ashr_i32 s4, s100, 4
	s_mul_hi_i32 s5, s4, 0x55555556
	s_lshr_b32 s6, s5, 31
	s_add_i32 s5, s5, s6
	s_mul_i32 s5, s5, 3
	s_sub_i32 s6, s4, s5
	s_mul_hi_i32 s4, s100, 0x2aaaaaab
	s_lshr_b32 s5, s4, 31
	s_ashr_i32 s4, s4, 3
	s_lshl_b32 s10, s6, 1
	s_add_i32 s7, s4, s5
	s_lshl_b32 s4, -1, s10
	s_andn2_b32 s9, s8, s4
	s_ashr_i32 s4, s7, 4
	s_ashr_i32 s5, s4, 31
	s_lshl_b64 s[4:5], s[4:5], 11
	s_or_b32 s4, s4, s9
	v_writelane_b32 v252, s4, 43
	s_mulk_i32 s6, 0xc00
	s_nop 0
	v_writelane_b32 v252, s5, 44
	s_lshl_b32 s4, s7, 6
	s_and_b32 s4, s4, 0x3c0
	s_lshr_b32 s5, s8, s10
	s_or_b32 s4, s6, s4
	v_writelane_b32 v252, s10, 45
	s_lshl_b32 s6, s5, 7
	s_ashr_i32 s5, s4, 31
	s_lshl_b64 s[4:5], s[4:5], 1
	v_writelane_b32 v252, s6, 46
	s_addk_i32 s6, 0xff80
	s_add_u32 s4, s34, s4
	v_writelane_b32 v252, s6, 47
	s_addc_u32 s5, s35, s5
	v_writelane_b32 v252, s4, 48
	s_nop 1
	v_writelane_b32 v252, s5, 49
	s_add_i32 s4, s84, s100
	s_cmpk_lt_i32 s4, 0xc00
	s_cselect_b64 s[6:7], -1, 0
	v_writelane_b32 v252, s6, 50
	s_ashr_i32 s5, s4, 4
	s_and_b32 s8, s4, 15
	v_writelane_b32 v252, s7, 51
	s_mul_hi_i32 s6, s5, 0x55555556
	s_lshr_b32 s7, s6, 31
	s_add_i32 s6, s6, s7
	s_mul_i32 s6, s6, 3
	s_sub_i32 s6, s5, s6
	s_mul_hi_i32 s5, s4, 0x2aaaaaab
	s_lshr_b32 s7, s5, 31
	s_ashr_i32 s5, s5, 3
	s_lshl_b32 s10, s6, 1
	s_add_i32 s7, s5, s7
	s_lshl_b32 s4, -1, s10
	s_andn2_b32 s9, s8, s4
	s_ashr_i32 s4, s7, 4
	s_ashr_i32 s5, s4, 31
	s_lshl_b64 s[4:5], s[4:5], 11
	s_or_b32 s4, s4, s9
	v_writelane_b32 v252, s4, 52
	s_mulk_i32 s6, 0xc00
	s_nop 0
	v_writelane_b32 v252, s5, 53
	s_lshl_b32 s4, s7, 6
	s_and_b32 s4, s4, 0x3c0
	s_lshr_b32 s5, s8, s10
	s_or_b32 s4, s6, s4
	v_writelane_b32 v252, s10, 54
	s_lshl_b32 s6, s5, 7
	s_ashr_i32 s5, s4, 31
	s_lshl_b64 s[4:5], s[4:5], 1
	v_writelane_b32 v252, s6, 55
	s_addk_i32 s6, 0xff80
	s_add_u32 s4, s34, s4
	v_writelane_b32 v252, s6, 56
	s_addc_u32 s5, s35, s5
	v_writelane_b32 v252, s4, 57
	s_lshl_b32 s2, s84, 1
	s_lshl_b32 s13, s84, 9
	v_writelane_b32 v252, s5, 58
	v_writelane_b32 v252, s2, 59
	s_add_u32 s2, s82, 0x20000
	s_addc_u32 s3, s83, 0
	v_writelane_b32 v252, s2, 60
	s_cmpk_lt_i32 s90, 0x100
	s_nop 0
	v_writelane_b32 v252, s3, 61
	s_cselect_b64 s[2:3], -1, 0
	v_writelane_b32 v252, s2, 62
	s_lshl_b32 s4, s1, 5
	s_nop 0
	v_writelane_b32 v252, s3, 63
	s_add_u32 s2, s82, 0x7700000
	s_addc_u32 s3, s83, 0
	v_writelane_b32 v253, s2, 0
	s_cmpk_lt_i32 s90, 0x300
	s_nop 0
	v_writelane_b32 v253, s3, 1
	s_cselect_b64 s[2:3], -1, 0
	v_writelane_b32 v253, s2, 2
	s_nop 1
	v_writelane_b32 v253, s3, 3
	s_and_b32 s2, s84, 7
	s_cmp_lg_u32 s2, 0
	s_cselect_b64 s[6:7], -1, 0
	s_cmp_eq_u32 s2, 0
	v_writelane_b32 v253, s6, 4
	s_cselect_b64 s[2:3], -1, 0
	s_cmpk_lt_i32 s90, 0x400
	v_writelane_b32 v253, s7, 5
	s_cselect_b64 s[6:7], -1, 0
	v_writelane_b32 v253, s6, 6
	s_and_b64 s[2:3], s[6:7], s[2:3]
	s_nop 0
	v_writelane_b32 v253, s7, 7
	v_writelane_b32 v253, s2, 8
	s_nop 1
	v_writelane_b32 v253, s3, 9
	s_lshl_b32 s2, s90, 7
	s_and_b32 s22, s2, 0x380
	v_writelane_b32 v253, s2, 10
	s_add_u32 s2, s82, 0x30000
	s_addc_u32 s3, s83, 0
	v_writelane_b32 v253, s2, 11
	s_nop 1
	v_writelane_b32 v253, s3, 12
	s_add_u32 s2, s82, 0x9700000
	s_addc_u32 s3, s83, 0
	v_writelane_b32 v253, s2, 13
	s_nop 1
	v_writelane_b32 v253, s3, 14
	s_add_u32 s2, s82, 0xb700000
	s_addc_u32 s3, s83, 0
	v_writelane_b32 v253, s2, 15
	s_lshl_b32 s5, s1, 7
	s_nop 0
	v_writelane_b32 v253, s3, 16
	s_add_u32 s2, s62, 0x1000
	s_addc_u32 s3, s63, 0
	v_writelane_b32 v253, s2, 17
	s_nop 1
	v_writelane_b32 v253, s3, 18
	s_add_u32 s2, s66, 0x400000
	s_addc_u32 s3, s67, 0
	v_writelane_b32 v253, s2, 19
	s_cmpk_lt_i32 s90, 0x800
	s_nop 0
	v_writelane_b32 v253, s3, 20
	s_cselect_b64 s[2:3], -1, 0
	v_writelane_b32 v253, s2, 21
	s_nop 1
	v_writelane_b32 v253, s3, 22
	s_ashr_i32 s2, s90, 8
	s_ashr_i32 s3, s2, 31
	s_lshl_b64 s[6:7], s[2:3], 11
	s_lshl_b32 s2, s90, 6
	s_and_b32 s2, s2, 0x7c0
	s_or_b32 s6, s6, s2
	v_writelane_b32 v253, s6, 23
	s_lshl_b32 s2, s90, 2
	s_and_b32 s2, s2, 0x380
	v_writelane_b32 v253, s7, 24
	v_writelane_b32 v253, s2, 25
	v_writelane_b32 v253, s51, 26
	v_sub_co_u32_e64 v0, s[2:3], s51, v0
	s_cmp_gt_i32 s90, 63
;     __host__ __device__ bool next(int i, Unit& u) const {
;         const long L = (long)i * G + c; if (L >= nwg) return false;
;         int wgid = (int)L; { const int q = nwg / NXCD, r = nwg % NXCD, xcd = wgid % NXCD, off = wgid / NXCD; wgid = (xcd < r ? xcd * (q + 1) : r * (q + 1) + (xcd - r) * q) + off; }
;         const int nig = WGM * nN, gid = wgid / nig, fm = gid * WGM, gsz = (nM - fm) < WGM ? (nM - fm) : WGM;
;         u.pm = fm + ((wgid % nig) % gsz); u.pn = (wgid % nig) / gsz; return true;
	s_nop 0
	v_writelane_b32 v253, s2, 27
	v_readlane_b32 s6, v251, 4
	s_nop 0
	v_writelane_b32 v253, s3, 28
	v_readfirstlane_b32 s2, v0
	s_cselect_b32 s2, s2, -1
	s_add_i32 s3, s6, 0xfffffe00
	s_cmp_gt_i32 s84, 64
	s_cselect_b32 s2, s2, s51
	s_cselect_b32 s3, s3, s6
	s_add_u32 s6, s58, 0x1000
	v_writelane_b32 v253, s3, 29
	s_addc_u32 s7, s59, 0
	v_writelane_b32 v253, s6, 30
	s_cmp_gt_i32 s2, -1
	s_mov_b64 s[50:51], s[14:15]
	v_writelane_b32 v253, s7, 31
	s_cselect_b64 s[6:7], -1, 0
	v_writelane_b32 v253, s6, 32
	s_cmpk_lt_u32 s2, 0x1400
	v_mov_b32_e32 v0, 0
	v_writelane_b32 v253, s7, 33
	s_cselect_b64 s[6:7], -1, 0
	v_writelane_b32 v253, s6, 34
	s_cmpk_lt_u32 s2, 0x200
	s_nop 0
	v_writelane_b32 v253, s7, 35
	s_cselect_b64 s[6:7], -1, 0
	v_writelane_b32 v253, s6, 36
	s_nop 1
	v_writelane_b32 v253, s7, 37
	s_add_u32 s6, s58, 0x2000
	s_addc_u32 s7, s59, 0
	v_writelane_b32 v253, s6, 38
	s_cmpk_lt_u32 s2, 0x600
	s_nop 0
	v_writelane_b32 v253, s7, 39
	s_cselect_b64 s[6:7], -1, 0
	v_writelane_b32 v253, s6, 40
	s_nop 1
	v_writelane_b32 v253, s7, 41
	s_add_u32 s6, s60, 0x1000000
	s_addc_u32 s7, s61, 0
	v_writelane_b32 v253, s6, 42
	s_nop 1
	v_writelane_b32 v253, s7, 43
	s_add_u32 s6, s58, 0x3000
	s_addc_u32 s7, s59, 0
	v_writelane_b32 v253, s6, 44
	s_cmpk_lt_u32 s2, 0x800
	s_nop 0
	v_writelane_b32 v253, s7, 45
	v_writelane_b32 v253, s2, 46
	s_cselect_b64 s[2:3], -1, 0
	v_writelane_b32 v253, s2, 47
	s_cmp_lt_i32 s90, 64
	s_nop 0
	v_writelane_b32 v253, s3, 48
	s_cselect_b64 s[2:3], -1, 0
	v_writelane_b32 v253, s2, 49
	s_cmp_lt_i32 s1, 0
	s_nop 0
	v_writelane_b32 v253, s3, 50
	s_mul_i32 s2, s1, 33
	s_cselect_b32 s2, s2, s4
	s_movk_i32 s4, 0xa1
	s_mul_i32 s3, s1, 0x81
	s_cselect_b32 s4, s4, 0xa0
	s_cselect_b32 s3, s3, s5
	s_mul_i32 s4, s1, s4
	s_movk_i32 s5, 0x61
	s_cselect_b32 s5, s5, 0x60
	s_add_i32 s4, s4, s0
	s_mul_hi_i32 s6, s4, 0x66666667
	s_lshr_b32 s7, s6, 31
	s_ashr_i32 s6, s6, 7
	s_add_i32 s6, s6, s7
	s_mul_i32 s7, s6, 0x140
	s_sub_i32 s4, s4, s7
	s_bfe_u32 s7, s4, 0x3001c
	s_add_i32 s7, s4, s7
	s_and_b32 s8, s7, 0xfff8
	s_add_i32 s2, s2, s0
	s_sub_i32 s4, s4, s8
	s_ashr_i32 s8, s2, 31
	s_lshr_b32 s8, s8, 27
	s_add_i32 s8, s2, s8
	s_and_b32 s9, s8, 0xffe0
	s_sub_i32 s2, s2, s9
	s_bfe_i32 s9, s2, 0x80000
	s_bfe_u32 s9, s9, 0x3000c
	s_mul_i32 s1, s1, s5
	s_add_i32 s9, s2, s9
	s_add_i32 s1, s1, s0
	s_and_b32 s10, s9, 0xf8
	s_mul_hi_i32 s5, s1, 0x2aaaaaab
	s_sub_i32 s2, s2, s10
	s_lshr_b32 s10, s5, 31
	s_ashr_i32 s5, s5, 4
	s_add_i32 s5, s5, s10
	s_mul_i32 s10, s5, 0x60
	s_sub_i32 s1, s1, s10
	s_bfe_i32 s10, s1, 0x80000
	s_add_i32 s0, s3, s0
	s_bfe_u32 s10, s10, 0x3000c
	s_ashr_i32 s3, s0, 31
	s_add_i32 s10, s1, s10
	s_lshr_b32 s3, s3, 25
	s_and_b32 s11, s10, 0xf8
	s_add_i32 s3, s0, s3
	s_sub_i32 s1, s1, s11
	s_and_b32 s11, s3, 0xff80
	s_sub_i32 s0, s0, s11
	s_bfe_i32 s11, s0, 0x80000
	s_lshl_b32 s6, s6, 3
	s_sext_i32_i16 s4, s4
	s_bfe_u32 s11, s11, 0x3000c
	s_add_i32 s26, s6, s4
	s_ashr_i32 s4, s8, 5
	s_add_i32 s11, s0, s11
	s_lshl_b32 s4, s4, 3
	s_sext_i32_i8 s2, s2
	s_and_b32 s12, s11, 0xf8
	s_add_i32 s30, s4, s2
	s_lshl_b32 s2, s5, 3
	s_sext_i32_i8 s1, s1
	s_sub_i32 s0, s0, s12
	s_bfe_i32 s4, s10, 0x80000
	s_add_i32 s10, s2, s1
	s_ashr_i32 s1, s3, 7
	s_sext_i32_i16 s7, s7
	s_bfe_i32 s6, s9, 0x80000
	s_lshl_b32 s1, s1, 3
	s_sext_i32_i8 s0, s0
	s_sext_i32_i16 s6, s6
	s_bfe_i32 s2, s11, 0x80000
	s_add_i32 s12, s1, s0
	s_ashr_i32 s0, s7, 3
	s_sext_i32_i16 s4, s4
	s_sext_i32_i16 s3, s2
	v_writelane_b32 v253, s0, 51
	s_ashr_i32 s2, s6, 3
	v_writelane_b32 v253, s2, 52
	s_ashr_i32 s5, s4, 3
	v_writelane_b32 v253, s5, 53
	s_ashr_i32 s5, s3, 3
	s_lshr_b32 s0, s7, 3
	v_writelane_b32 v253, s5, 54
	s_mov_b32 s8, s26
	s_ashr_i32 s27, s26, 31
	s_bfe_i64 s[0:1], s[0:1], 0x100000
	v_writelane_b32 v253, s8, 55
	s_lshl_b64 s[0:1], s[0:1], 19
	s_lshr_b32 s2, s6, 3
	s_lshr_b32 s4, s4, 3
	s_lshr_b32 s6, s3, 3
	v_writelane_b32 v253, s9, 56
	s_lshl_b64 s[8:9], s[26:27], 19
	s_add_u32 s0, s52, s0
	v_writelane_b32 v253, s8, 57
	s_addc_u32 s1, s53, s1
	s_mov_b32 s27, 0
	v_writelane_b32 v253, s9, 58
	s_add_u32 s8, s0, 0x40000
	s_addc_u32 s9, s1, 0
	v_writelane_b32 v253, s8, 59
	s_mov_b32 s23, s27
	s_nop 0
	v_writelane_b32 v253, s9, 60
	s_add_u32 s8, s0, 0x40080
	v_writelane_b32 v253, s0, 61
	s_addc_u32 s9, s1, 0
	s_ashr_i32 s31, s30, 31
	v_writelane_b32 v253, s1, 62
	v_writelane_b32 v253, s8, 63
	s_bfe_i64 s[0:1], s[2:3], 0x100000
	s_mov_b32 s2, s30
	v_writelane_b32 v254, s9, 0
	v_writelane_b32 v254, s2, 1
	s_lshl_b64 s[0:1], s[0:1], 19
	s_nop 0
	v_writelane_b32 v254, s3, 2
	s_lshl_b64 s[2:3], s[30:31], 19
	s_add_u32 s8, s16, s0
	v_writelane_b32 v254, s16, 3
	s_addc_u32 s9, s17, s1
	s_nop 0
	v_writelane_b32 v254, s17, 4
	s_add_u32 s16, s8, 0x40000
	s_addc_u32 s17, s9, 0
;     __host__ __device__ bool next(int i, Unit& u) const {
;         const long L = (long)i * G + c; if (L >= nwg) return false;
;         int wgid = (int)L; { const int q = nwg / NXCD, r = nwg % NXCD, xcd = wgid % NXCD, off = wgid / NXCD; wgid = (xcd < r ? xcd * (q + 1) : r * (q + 1) + (xcd - r) * q) + off; }
;         const int nig = WGM * nN, gid = wgid / nig, fm = gid * WGM, gsz = (nM - fm) < WGM ? (nM - fm) : WGM;
;         u.pm = fm + ((wgid % nig) % gsz); u.pn = (wgid % nig) / gsz; return true;
; template <class Epi, class Sched, bool ALIGN_EPI = false, bool SP2 = false>
; __device__ __forceinline__ void gemm_phase(PG8_LAS unsigned char* lds, const Gemm g, const Sched& S, const Epi& E) {
;     ...
;     const char* cA = (const char*)g.A + (size_t)cur.pm * tstep; const char* cB = (const char*)g.Bt + (size_t)cur.pn * tstep;
	v_writelane_b32 v254, s16, 5
	s_add_u32 s2, s14, s2
	s_addc_u32 s3, s15, s3
	v_writelane_b32 v254, s17, 6
	s_add_u32 s16, s2, 0x40000
	v_writelane_b32 v254, s2, 7
	s_addc_u32 s17, s3, 0
	s_nop 0
	v_writelane_b32 v254, s3, 8
	v_writelane_b32 v254, s16, 9
	s_add_u32 s2, s8, 0x40080
	s_nop 0
	v_writelane_b32 v254, s17, 10
	v_writelane_b32 v254, s8, 11
	s_addc_u32 s3, s9, 0
	s_ashr_i32 s11, s10, 31
	v_writelane_b32 v254, s9, 12
	v_writelane_b32 v254, s2, 13
	s_mov_b64 s[16:17], 0x80
	s_nop 0
	v_writelane_b32 v254, s3, 14
	s_bfe_i64 s[2:3], s[4:5], 0x100000
	s_mov_b32 s4, s10
	v_writelane_b32 v254, s4, 15
	s_lshl_b64 s[2:3], s[2:3], 19
	s_nop 0
	v_writelane_b32 v254, s5, 16
	s_lshl_b64 s[4:5], s[10:11], 19
	s_add_u32 s2, s18, s2
	v_writelane_b32 v254, s18, 17
	s_addc_u32 s3, s19, s3
	s_add_u32 s8, s2, 0x40000
	v_writelane_b32 v254, s19, 18
	s_addc_u32 s9, s3, 0
	v_writelane_b32 v254, s8, 19
	s_add_u32 s4, s54, s4
	s_addc_u32 s5, s55, s5
	v_writelane_b32 v254, s9, 20
	s_add_u32 s8, s4, 0x40000
	v_writelane_b32 v254, s4, 21
	s_addc_u32 s9, s5, 0
	s_nop 0
	v_writelane_b32 v254, s5, 22
	v_writelane_b32 v254, s8, 23
	s_add_u32 s4, s2, 0x40080
	s_nop 0
	v_writelane_b32 v254, s9, 24
	v_writelane_b32 v254, s2, 25
	s_addc_u32 s5, s3, 0
	s_mov_b64 s[8:9], s[64:65]
	v_writelane_b32 v254, s3, 26
	v_writelane_b32 v254, s4, 27
	s_add_u32 s2, s20, s0
	s_nop 0
	v_writelane_b32 v254, s5, 28
	v_writelane_b32 v254, s20, 29
	s_addc_u32 s3, s21, s1
	s_add_u32 s4, s2, 0x40000
	v_writelane_b32 v254, s21, 30
	s_addc_u32 s5, s3, 0
	v_writelane_b32 v254, s4, 31
	s_mov_b32 s20, s13
	s_mov_b32 s21, 0x100000
	v_writelane_b32 v254, s5, 32
	s_add_u32 s4, s2, 0x40080
	v_writelane_b32 v254, s2, 33
	s_addc_u32 s5, s3, 0
	s_ashr_i32 s13, s12, 31
	v_writelane_b32 v254, s3, 34
	v_writelane_b32 v254, s4, 35
	s_bfe_i64 s[2:3], s[6:7], 0x100000
	s_lshl_b64 s[2:3], s[2:3], 19
	v_writelane_b32 v254, s5, 36
	v_writelane_b32 v254, s2, 37
	s_mov_b64 s[6:7], s[62:63]
	s_nop 0
	v_writelane_b32 v254, s3, 38
	s_mov_b32 s2, s12
	v_writelane_b32 v254, s2, 39
	s_nop 1
	v_writelane_b32 v254, s3, 40
	s_lshl_b64 s[2:3], s[12:13], 19
	s_add_u32 s2, s54, s2
	s_addc_u32 s3, s55, s3
	s_add_u32 s4, s2, 0x40000
	v_writelane_b32 v254, s2, 41
	s_addc_u32 s5, s3, 0
	s_mov_b64 s[12:13], s[68:69]
	v_writelane_b32 v254, s3, 42
	v_readlane_b32 s2, v251, 0
	v_writelane_b32 v254, s4, 43
	s_add_u32 s2, s2, s0
	s_mul_i32 s0, s85, s84
	v_writelane_b32 v254, s5, 44
	v_readlane_b32 s3, v251, 1
	s_mul_i32 s0, s0, s33
	s_addc_u32 s3, s3, s1
	v_writelane_b32 v254, s0, 45
	v_writelane_b32 v254, s22, 46
	s_add_u32 s0, s2, 0x40000
	s_addc_u32 s1, s3, 0
	v_writelane_b32 v254, s23, 47
	v_writelane_b32 v254, s0, 48
	s_mov_b64 s[14:15], s[70:71]
	s_mov_b32 s33, 0x800000
	v_writelane_b32 v254, s1, 49
	s_add_u32 s0, s2, 0x40080
	v_writelane_b32 v254, s2, 50
	s_addc_u32 s1, s3, 0
	s_mov_b32 s85, s20
	v_writelane_b32 v254, s3, 51
	v_writelane_b32 v254, s0, 52
	s_mov_b64 s[2:3], -1
	s_nop 0
	v_writelane_b32 v254, s1, 53
	s_lshl_b32 s0, s84, 7
	v_writelane_b32 v254, s0, 54
	s_add_i32 s0, 0, 0x27fc0
	v_writelane_b32 v254, s0, 55
	s_add_i32 s0, 0, 0x27fc4
	v_writelane_b32 v254, s0, 56
	s_add_i32 s0, 0, 0x8800
	v_writelane_b32 v254, s0, 57
	s_add_i32 s0, 0, 0xee00
	v_writelane_b32 v254, s0, 58
	s_add_i32 s0, 0, 0xcc00
	v_writelane_b32 v254, s0, 59
	s_add_i32 s0, 0, 0x9900
	v_writelane_b32 v254, s0, 60
	s_add_i32 s0, 0, 0xdd00
	v_writelane_b32 v254, s0, 61
	s_add_i32 s0, 0, 0x1f400
	v_writelane_b32 v254, s0, 62
	s_add_i32 s0, 0, 0x23800
	v_writelane_b32 v254, s0, 63
	s_add_i32 s0, 0, 0x1ec00
	v_writelane_b32 v255, s0, 0
	s_mov_b32 s0, 0
	v_writelane_b32 v255, s0, 1
	v_cmp_gt_i32_e64 s[0:1], s21, v138
	s_nop 1
	v_writelane_b32 v255, s0, 2
	s_nop 1
	v_writelane_b32 v255, s1, 3
	s_mov_b64 s[0:1], s[56:57]
	v_writelane_b32 v255, s0, 4
	s_nop 1
	v_writelane_b32 v255, s1, 5
	v_writelane_b32 v255, s2, 6
	v_writelane_b32 v255, s3, 7
	v_writelane_b32 v255, s4, 8
	v_writelane_b32 v255, s5, 9
	v_writelane_b32 v255, s6, 10
	v_writelane_b32 v255, s7, 11
	v_writelane_b32 v255, s8, 12
	v_writelane_b32 v255, s9, 13
	v_writelane_b32 v255, s10, 14
	v_writelane_b32 v255, s11, 15
	v_writelane_b32 v255, s12, 16
	v_writelane_b32 v255, s13, 17
	v_writelane_b32 v255, s14, 18
	v_writelane_b32 v255, s15, 19
	v_writelane_b32 v255, s52, 20
	s_nop 1
	v_writelane_b32 v255, s53, 21
	v_writelane_b32 v255, s54, 22
	s_nop 1
	v_writelane_b32 v255, s55, 23
	v_writelane_b32 v255, s50, 24
	s_nop 1
	v_writelane_b32 v255, s51, 25
	v_writelane_b32 v255, s24, 26
	s_nop 1
	v_writelane_b32 v255, s25, 27
	v_writelane_b32 v255, s28, 28
	s_nop 1
	v_writelane_b32 v255, s29, 29
	v_writelane_b32 v255, s90, 30
	v_writelane_b32 v255, s86, 31
	s_nop 1
	v_writelane_b32 v255, s87, 32
	s_branch .LBB0_113

; #define LAS __attribute__((address_space(3)))
; __device__ __forceinline__ f32x4 mfma16(bf16x8 a, bf16x8 b, f32x4 c) { return __builtin_amdgcn_mfma_f32_16x16x32_bf16(a, b, c, 0, 0, 0); }
; __device__ __forceinline__ void attn_phase(LAS unsigned char* lds, const bf16* PROJ, const bf16* Ygate, bf16* OG0, bf16* OG1, bf16* OG2, float* LSE, const float* qnw, const float* knw, int bx, int G) {
;     ...
;     const int tid = tid_l, lane = tid & 63, w = __builtin_amdgcn_readfirstlane(tid >> 6), l16 = lane & 15, g4 = lane >> 4;
;     LAS bf16* Ks = (LAS bf16*)(lds + AT_KS); LAS bf16* Vs = (LAS bf16*)(lds + AT_VS);
;     const int oct = tid & 7;
;     v4u kr[2][4], vr[2][4], qr[2][2];
;     ...
;         const int qi = 16 * w + l16;
;     ...
;         const int tlo = (n == 0) ? 8 : 0;
;         f32x4 sc[9]; float mx = -3.0e38f;
; #pragma unroll
;         for (int t9 = 0; t9 < 9; ++t9) {
;             const int T = w + t9;
;             if (T >= tlo) {
;                 f32x4 a4 = (f32x4){0.f, 0.f, 0.f, 0.f};
; #pragma unroll
;                 for (int ks = 0; ks < 2; ++ks) { const bf16x8 a = *(const LAS bf16x8*)(Ks + (16 * T + l16) * 72 + 32 * ks + 8 * g4); a4 = mfma16(a, qreg[ks], a4); }
; #pragma unroll
;                 for (int rr = 0; rr < 4; ++rr) {
;                     const int kj = 16 * T + 4 * g4 + rr; const int dist = 128 + qi - kj;
;                     const bool valid = (dist >= 0) && (dist <= 128);
;                     const float sv = valid ? (a4[rr] - ad * (float)dist) : -1e30f;
;                     sc[t9][rr] = sv; mx = fmaxf(mx, sv);
;                 }
;             } else sc[t9] = (f32x4){-1e30f, -1e30f, -1e30f, -1e30f};
.LBB0_265:
	s_lshl_b32 s2, s22, 1
	v_readlane_b32 s4, v255, 24
	v_readlane_b32 s5, v255, 25
	s_add_u32 s28, s4, s2
	s_addc_u32 s29, s5, 0
	s_and_b64 vcc, exec, s[0:1]
	s_cbranch_vccnz .LBB0_353
	v_readlane_b32 s0, v251, 5
	v_lshlrev_b32_e32 v2, 5, v87
	v_mov_b32_e32 v3, v0
	v_readlane_b32 s1, v251, 6
	v_lshlrev_b32_e32 v85, 4, v85
	v_lshlrev_b32_e32 v112, 3, v86
	v_lshl_add_u64 v[110:111], s[0:1], 0, v[2:3]
	v_lshlrev_b32_e32 v2, 5, v86
	v_lshl_add_u64 v[114:115], s[70:71], 0, v[2:3]
	v_lshl_add_u32 v183, v86, 4, 0
	v_lshlrev_b32_e32 v2, 2, v86
	v_and_b32_e32 v85, 48, v85
	v_cmp_eq_u32_e64 s[40:41], 0, v86
	v_and_b32_e32 v86, 64, v191
	v_add_u32_e32 v184, 0, v85
	v_xor_b32_e32 v85, 1, v191
	v_add_u32_e32 v86, 64, v86
	v_cmp_lt_i32_e32 vcc, v85, v86
	v_xor_b32_e32 v88, 16, v191
	s_lshl_b32 s0, s50, 4
	v_cndmask_b32_e32 v85, v191, v85, vcc
	v_lshlrev_b32_e32 v185, 2, v85
	v_xor_b32_e32 v85, 2, v191
	v_cmp_lt_i32_e32 vcc, v85, v86
	v_or_b32_e32 v147, s0, v84
	v_readlane_b32 s14, v251, 19
	v_cndmask_b32_e32 v85, v191, v85, vcc
	v_lshlrev_b32_e32 v186, 2, v85
	v_xor_b32_e32 v85, 4, v191
	v_cmp_lt_i32_e32 vcc, v85, v86
	v_add_u32_e32 v1, 0x80, v147
	v_readlane_b32 s2, v251, 7
	v_cndmask_b32_e32 v85, v191, v85, vcc
	v_cmp_lt_i32_e32 vcc, v88, v86
	v_readlane_b32 s3, v251, 8
	s_movk_i32 s14, 0x81
	v_cndmask_b32_e32 v88, v191, v88, vcc
	v_lshlrev_b32_e32 v189, 2, v88
	v_xor_b32_e32 v88, 32, v191
	v_cmp_lt_i32_e32 vcc, v88, v86
	s_add_i32 s43, s50, 1
	s_lshl_b32 s1, s43, 4
	v_cndmask_b32_e32 v86, v191, v88, vcc
	v_lshlrev_b32_e32 v196, 2, v86
	v_or_b32_e32 v86, s0, v2
	v_sub_u32_e32 v88, v1, v86
	v_cmp_gt_u32_e64 s[2:3], s14, v88
	v_cvt_f32_u32_e32 v198, v88
	v_xad_u32 v88, v86, -1, v1
	v_writelane_b32 v255, s2, 37
	v_cvt_f32_u32_e32 v199, v88
	s_add_i32 s44, s50, 2
	v_writelane_b32 v255, s3, 38
	v_cmp_gt_u32_e64 s[2:3], s14, v88
	v_or_b32_e32 v88, 3, v86
	v_sub_u32_e32 v88, v1, v88
	v_writelane_b32 v255, s2, 39
	v_or_b32_e32 v86, 2, v86
	v_sub_u32_e32 v86, v1, v86
	v_writelane_b32 v255, s3, 40
	v_cmp_gt_u32_e64 s[2:3], s14, v88
	v_cvt_f32_u32_e32 v116, v86
	v_cvt_f32_u32_e32 v117, v88
	v_writelane_b32 v255, s2, 41
	s_add_i32 s45, s50, 3
	s_add_i32 s46, s50, 4
	v_writelane_b32 v255, s3, 42
	v_cmp_gt_u32_e64 s[2:3], s14, v86
	v_or_b32_e32 v86, s1, v84
	v_mul_lo_u32 v200, v86, s91
	v_or_b32_e32 v86, s1, v2
	v_writelane_b32 v255, s2, 43
	v_sub_u32_e32 v88, v1, v86
	v_cvt_f32_u32_e32 v201, v88
	v_writelane_b32 v255, s3, 44
	v_cmp_gt_u32_e64 s[2:3], s14, v88
	v_xad_u32 v88, v86, -1, v1
	v_cvt_f32_u32_e32 v202, v88
	v_writelane_b32 v255, s2, 45
	s_lshl_b32 s1, s44, 4
	s_add_i32 s47, s50, 5
	v_writelane_b32 v255, s3, 46
	v_cmp_gt_u32_e64 s[2:3], s14, v88
	v_or_b32_e32 v88, 3, v86
	v_sub_u32_e32 v88, v1, v88
	v_writelane_b32 v255, s2, 47
	v_or_b32_e32 v86, 2, v86
	v_sub_u32_e32 v86, v1, v86
	v_writelane_b32 v255, s3, 48
	v_cmp_gt_u32_e64 s[2:3], s14, v88
	v_cvt_f32_u32_e32 v118, v86
	v_cvt_f32_u32_e32 v119, v88
	v_writelane_b32 v255, s2, 49
	v_lshrrev_b32_e32 v3, 2, v84
	v_or_b32_e32 v3, v2, v3
	v_writelane_b32 v255, s3, 50
	v_cmp_gt_u32_e64 s[2:3], s14, v86
	v_or_b32_e32 v86, s1, v84
	v_mul_lo_u32 v203, v86, s91
	v_or_b32_e32 v86, s1, v2
	v_writelane_b32 v255, s2, 51
	v_sub_u32_e32 v88, v1, v86
	v_cvt_f32_u32_e32 v204, v88
	v_writelane_b32 v255, s3, 52
	v_cmp_gt_u32_e64 s[2:3], s14, v88
	v_xad_u32 v88, v86, -1, v1
	v_cvt_f32_u32_e32 v205, v88
	v_writelane_b32 v255, s2, 53
	s_add_i32 s48, s50, 7
	s_add_i32 s49, s50, 6
	v_writelane_b32 v255, s3, 54
	v_cmp_gt_u32_e64 s[2:3], s14, v88
	v_or_b32_e32 v88, 3, v86
	v_sub_u32_e32 v88, v1, v88
	v_writelane_b32 v255, s2, 55
	v_or_b32_e32 v86, 2, v86
	v_sub_u32_e32 v86, v1, v86
	v_writelane_b32 v255, s3, 56
	v_cmp_gt_u32_e64 s[2:3], s14, v88
	v_cvt_f32_u32_e32 v120, v86
	v_cvt_f32_u32_e32 v121, v88
	v_writelane_b32 v255, s2, 57
	s_add_i32 s42, s50, 8
	v_or_b32_e32 v91, s0, v3
	v_writelane_b32 v255, s3, 58
	v_cmp_gt_u32_e64 s[2:3], s14, v86
	s_lshl_b32 s0, s49, 4
	v_or_b32_e32 v94, s1, v3
	v_writelane_b32 v255, s2, 59
	s_lshl_b32 s1, s42, 4
	v_or_b32_e32 v92, s0, v84
	v_writelane_b32 v255, s3, 60
	s_lshl_b32 s2, s45, 4
	v_or_b32_e32 v86, s2, v84
	v_mul_lo_u32 v206, v86, s91
	v_or_b32_e32 v86, s2, v2
	v_sub_u32_e32 v88, v1, v86
	v_cmp_gt_u32_e64 s[66:67], s14, v88
	v_cvt_f32_u32_e32 v207, v88
	v_xad_u32 v88, v86, -1, v1
	v_cmp_gt_u32_e64 s[68:69], s14, v88
	v_cvt_f32_u32_e32 v208, v88
	v_or_b32_e32 v88, 3, v86
	v_or_b32_e32 v86, 2, v86
	v_sub_u32_e32 v86, v1, v86
	s_lshl_b32 s2, s46, 4
	v_cmp_gt_u32_e64 s[72:73], s14, v86
	v_cvt_f32_u32_e32 v122, v86
	v_or_b32_e32 v86, s2, v84
	v_sub_u32_e32 v88, v1, v88
	v_mul_lo_u32 v209, v86, s91
	v_or_b32_e32 v86, s2, v2
	v_cmp_gt_u32_e64 s[70:71], s14, v88
	v_cvt_f32_u32_e32 v123, v88
	v_sub_u32_e32 v88, v1, v86
	v_cmp_gt_u32_e64 s[74:75], s14, v88
	v_cvt_f32_u32_e32 v210, v88
	v_xad_u32 v88, v86, -1, v1
	v_cmp_gt_u32_e64 s[76:77], s14, v88
	v_cvt_f32_u32_e32 v211, v88
	v_or_b32_e32 v88, 3, v86
	v_or_b32_e32 v86, 2, v86
	v_sub_u32_e32 v86, v1, v86
	s_lshl_b32 s3, s47, 4
	v_cmp_gt_u32_e64 s[56:57], s14, v86
	v_cvt_f32_u32_e32 v124, v86
	v_or_b32_e32 v86, s3, v84
	v_sub_u32_e32 v88, v1, v88
	v_mul_lo_u32 v212, v86, s91
	v_or_b32_e32 v86, s3, v2
	v_cmp_gt_u32_e64 s[78:79], s14, v88
	v_cvt_f32_u32_e32 v125, v88
	v_sub_u32_e32 v88, v1, v86
	v_cmp_gt_u32_e64 s[58:59], s14, v88
	v_cvt_f32_u32_e32 v213, v88
	v_xad_u32 v88, v86, -1, v1
	v_cmp_gt_u32_e64 s[64:65], s14, v88
	v_cvt_f32_u32_e32 v214, v88
	v_or_b32_e32 v88, 3, v86
	v_or_b32_e32 v86, 2, v86
	s_lshl_b32 s3, s48, 4
	v_sub_u32_e32 v86, v1, v86
	v_sub_u32_e32 v88, v1, v88
	v_or_b32_e32 v89, s3, v84
	v_or_b32_e32 v90, s3, v2
	v_or_b32_e32 v93, s0, v2
	v_or_b32_e32 v84, s1, v84
	v_or_b32_e32 v2, s1, v2
	v_cmp_gt_u32_e64 s[86:87], s14, v88
	v_cmp_gt_u32_e64 s[88:89], s14, v86
	v_cvt_f32_u32_e32 v127, v88
	v_cvt_f32_u32_e32 v126, v86
	v_mul_lo_u32 v215, v92, s91
	v_sub_u32_e32 v86, v1, v93
	v_xad_u32 v88, v93, -1, v1
	v_or_b32_e32 v92, 3, v93
	v_or_b32_e32 v93, 2, v93
	v_mul_lo_u32 v218, v89, s91
	v_sub_u32_e32 v89, v1, v90
	s_waitcnt vmcnt(2)
; __device__ __forceinline__ void attn_phase(LAS unsigned char* lds, const bf16* PROJ, const bf16* Ygate, bf16* OG0, bf16* OG1, bf16* OG2, float* LSE, const float* qnw, const float* knw, int bx, int G) {
;     ...
;     for (int t2 = bx; t2 < 3072; t2 += 2 * G) {
; #pragma unroll
;     for (int half = 0; half < 2; ++half) {
;         const int t = t2 + half * G;
;         if (t < 3072) {
;         const int sub = t & 15, gi = (t >> 4) % 3, bh = t / 48, h = bh & 15, bl = bh >> 4;
	v_xad_u32 v97, v90, -1, v1
	s_waitcnt vmcnt(0)
	v_or_b32_e32 v98, 3, v90
	v_or_b32_e32 v90, 2, v90
	v_mul_lo_u32 v221, v84, s91
	v_sub_u32_e32 v84, v1, v2
	v_xad_u32 v99, v2, -1, v1
	v_or_b32_e32 v100, 3, v2
	v_or_b32_e32 v2, 2, v2
	v_readlane_b32 s4, v251, 9
	v_sub_u32_e32 v93, v1, v93
	v_sub_u32_e32 v92, v1, v92
	v_sub_u32_e32 v90, v1, v90
	v_sub_u32_e32 v98, v1, v98
	v_sub_u32_e32 v2, v1, v2
	v_sub_u32_e32 v1, v1, v100
	s_movk_i32 s4, 0xa0
	v_cvt_f32_u32_e32 v216, v86
	v_cvt_f32_u32_e32 v217, v88
	v_cvt_f32_u32_e32 v129, v92
	v_cvt_f32_u32_e32 v128, v93
	v_cvt_f32_u32_e32 v219, v89
	v_cvt_f32_u32_e32 v220, v97
	v_cvt_f32_u32_e32 v131, v98
	v_cvt_f32_u32_e32 v130, v90
	v_cvt_f32_u32_e32 v222, v84
	v_cvt_f32_u32_e32 v223, v99
	v_cvt_f32_u32_e32 v133, v1
	v_cvt_f32_u32_e32 v132, v2
	v_mul_lo_u32 v188, v109, s4
	s_mov_b64 s[60:61], s[80:81]
	v_readlane_b32 s5, v251, 10
	v_readlane_b32 s6, v251, 11
	v_readlane_b32 s7, v251, 12
	v_readlane_b32 s8, v251, 13
	v_readlane_b32 s9, v251, 14
	v_readlane_b32 s10, v251, 15
	v_readlane_b32 s11, v251, 16
	v_readlane_b32 s12, v251, 17
	v_readlane_b32 s13, v251, 18
	v_readlane_b32 s15, v251, 20
	v_lshl_add_u32 v113, v87, 4, 0
	v_lshlrev_b32_e32 v187, 2, v85
	v_mul_lo_u32 v85, v109, s91
	v_add_u32_e32 v87, 0x2800, v188
	v_or_b32_e32 v95, s2, v3
	v_or_b32_e32 v96, s0, v3
	v_or_b32_e32 v3, s1, v3
	v_mov_b64_e32 v[160:161], 0xff
	s_mov_b64 s[62:63], s[82:83]
	v_add_u32_e32 v182, 0xffffff80, v109
	v_mul_lo_u32 v197, v147, s91
	v_mul_lo_u32 v224, v91, s4
	v_mul_lo_u32 v225, v94, s4
	v_mul_lo_u32 v226, v95, s4
	v_mul_lo_u32 v227, v96, s4
	v_mul_lo_u32 v228, v3, s4
	v_add_u32_e32 v229, v113, v85
	v_add_u32_e32 v230, v113, v87
	s_lshr_b32 s51, s90, 3
	s_and_b32 s51, s51, 15
	s_and_b32 s101, s90, 7
	s_lshl_b32 s101, s101, 4
	s_or_b32 s51, s51, s101
	s_and_b32 s101, s90, 0x80
	s_or_b32 s51, s51, s101
	s_cmp_eq_u32 s84, 0x100
	s_cselect_b32 s51, s51, s90
	v_cmp_gt_u32_e64 s[90:91], s14, v86
	v_cmp_gt_u32_e64 s[92:93], s14, v88
	v_cmp_gt_u32_e64 s[94:95], s14, v92
	v_cmp_gt_u32_e64 s[96:97], s14, v93
	v_cmp_gt_u32_e64 s[36:37], s14, v89
	v_cmp_gt_u32_e64 s[18:19], s14, v97
	v_cmp_gt_u32_e64 s[4:5], s14, v98
	v_cmp_gt_u32_e64 s[6:7], s14, v90
	v_cmp_gt_u32_e64 s[8:9], s14, v84
	v_cmp_gt_u32_e64 s[10:11], s14, v99
	v_cmp_gt_u32_e64 s[12:13], s14, v1
	v_cmp_gt_u32_e64 s[14:15], s14, v2
	s_branch .LBB0_269
